# baseline (speedup 1.0000x reference)
; DEVI unsigned cvtpk(float lo, float hi) { unsigned r; asm("v_cvt_pk_bf16_f32 %0, %1, %2" : "=v"(r) : "v"(lo), "v"(hi)); return r; }
; DEVI int crow(int r, int hi) { return (r & 3) + 8 * (r >> 2) + 4 * hi; }
; DEVI float xor1(float v) { return dppf<0xB1, 0xF>(v, v); }
; template <class RowPtr> DEVI void store2_bf16(const f32x16& a0, const f32x16& a1, char* slice, int lane, int col0, RowPtr rowptr) {
;   const int r32 = lane & 31, hi = lane >> 5; const bool odd = r32 & 1;
; #pragma unroll
;   for (int jj = 0; jj < 2; ++jj) {
; #pragma unroll
;     for (int r = 0; r < 16; r += 2) {
;       const float x0 = jj ? a1[r] : a0[r], x1 = jj ? a1[r + 1] : a0[r + 1];
;       const float send = odd ? x0 : x1;
;       const float recv = xor1(send);
;       const unsigned pk = odd ? cvtpk(recv, x1) : cvtpk(x0, recv);
;       const int rr = crow(odd ? r + 1 : r, hi);
;       *(unsigned*)(slice + rr * 128 + (jj * 32 + (r32 & ~1)) * 2) = pk;
;     }
;   }
; #pragma unroll
;   for (int ps = 0; ps < 4; ++ps) {
;     const int row = ps * 8 + (lane >> 3), ch = lane & 7;
;     const u32x4 v = *(const u32x4*)(slice + row * 128 + ch * 16);
;     *(u32x4*)(rowptr(row) + col0 + ch * 8) = v;
;   }
.LBB0_220:
	v_cndmask_b32_e64 v124, v50, v51, s[38:39]
	s_nop 1
	v_mov_b32_dpp v124, v124 quad_perm:[1,0,3,2] row_mask:0xf bank_mask:0xf
	v_cndmask_b32_e64 v125, v50, v124, s[40:41]
	v_cndmask_b32_e64 v124, v124, v51, s[40:41]
	v_cvt_pk_bf16_f32 v125, v125, v124
	v_cndmask_b32_e64 v50, v52, v53, s[38:39]
	ds_write_b32 v152, v125 offset:49152
	s_nop 0
	v_mov_b32_dpp v50, v50 quad_perm:[1,0,3,2] row_mask:0xf bank_mask:0xf
	v_cndmask_b32_e64 v51, v52, v50, s[40:41]
	v_cndmask_b32_e64 v50, v50, v53, s[40:41]
	v_cvt_pk_bf16_f32 v51, v51, v50
	v_cndmask_b32_e64 v50, v54, v55, s[38:39]
	ds_write_b32 v152, v51 offset:49408
	s_nop 0
	v_mov_b32_dpp v50, v50 quad_perm:[1,0,3,2] row_mask:0xf bank_mask:0xf
	v_cndmask_b32_e64 v51, v54, v50, s[40:41]
	v_cndmask_b32_e64 v50, v50, v55, s[40:41]
	v_cvt_pk_bf16_f32 v51, v51, v50
	v_cndmask_b32_e64 v50, v56, v57, s[38:39]
	ds_write_b32 v152, v51 offset:50176
	s_nop 0
	v_mov_b32_dpp v50, v50 quad_perm:[1,0,3,2] row_mask:0xf bank_mask:0xf
	v_cndmask_b32_e64 v51, v56, v50, s[40:41]
	v_cndmask_b32_e64 v50, v50, v57, s[40:41]
	v_cvt_pk_bf16_f32 v51, v51, v50
	v_cndmask_b32_e64 v50, v58, v59, s[38:39]
	ds_write_b32 v152, v51 offset:50432
	s_nop 0
	v_mov_b32_dpp v50, v50 quad_perm:[1,0,3,2] row_mask:0xf bank_mask:0xf
	v_cndmask_b32_e64 v51, v58, v50, s[40:41]
	v_cndmask_b32_e64 v50, v50, v59, s[40:41]
	v_cvt_pk_bf16_f32 v51, v51, v50
	v_cndmask_b32_e64 v50, v60, v61, s[38:39]
	ds_write_b32 v152, v51 offset:51200
	s_nop 0
	v_mov_b32_dpp v50, v50 quad_perm:[1,0,3,2] row_mask:0xf bank_mask:0xf
	v_cndmask_b32_e64 v51, v60, v50, s[40:41]
	v_cndmask_b32_e64 v50, v50, v61, s[40:41]
	v_cvt_pk_bf16_f32 v51, v51, v50
	v_cndmask_b32_e64 v50, v62, v63, s[38:39]
	ds_write_b32 v152, v51 offset:51456
	s_nop 0
	v_mov_b32_dpp v50, v50 quad_perm:[1,0,3,2] row_mask:0xf bank_mask:0xf
	v_cndmask_b32_e64 v51, v62, v50, s[40:41]
	v_cndmask_b32_e64 v50, v50, v63, s[40:41]
	v_cvt_pk_bf16_f32 v51, v51, v50
	v_cndmask_b32_e64 v50, v64, v65, s[38:39]
	ds_write_b32 v152, v51 offset:52224
	s_nop 0
	v_mov_b32_dpp v50, v50 quad_perm:[1,0,3,2] row_mask:0xf bank_mask:0xf
	v_cndmask_b32_e64 v124, v64, v50, s[40:41]
	v_cndmask_b32_e64 v50, v50, v65, s[40:41]
	v_cvt_pk_bf16_f32 v124, v124, v50
	v_cndmask_b32_e64 v50, v34, v35, s[38:39]
	ds_write_b32 v152, v124 offset:52480
	s_nop 0
	v_mov_b32_dpp v50, v50 quad_perm:[1,0,3,2] row_mask:0xf bank_mask:0xf
	v_cndmask_b32_e64 v51, v34, v50, s[40:41]
	v_cndmask_b32_e64 v50, v50, v35, s[40:41]
	v_cvt_pk_bf16_f32 v51, v51, v50
	v_cndmask_b32_e64 v34, v36, v37, s[38:39]
	ds_write_b32 v152, v51 offset:49216
	s_nop 0
	v_mov_b32_dpp v34, v34 quad_perm:[1,0,3,2] row_mask:0xf bank_mask:0xf
	v_cndmask_b32_e64 v35, v36, v34, s[40:41]
	v_cndmask_b32_e64 v34, v34, v37, s[40:41]
	v_cvt_pk_bf16_f32 v35, v35, v34
	v_cndmask_b32_e64 v34, v38, v39, s[38:39]
	ds_write_b32 v152, v35 offset:49472
	s_nop 0
	v_mov_b32_dpp v34, v34 quad_perm:[1,0,3,2] row_mask:0xf bank_mask:0xf
	v_cndmask_b32_e64 v35, v38, v34, s[40:41]
	v_cndmask_b32_e64 v34, v34, v39, s[40:41]
	v_cvt_pk_bf16_f32 v35, v35, v34
	v_cndmask_b32_e64 v34, v40, v41, s[38:39]
	ds_write_b32 v152, v35 offset:50240
	s_nop 0
	v_mov_b32_dpp v34, v34 quad_perm:[1,0,3,2] row_mask:0xf bank_mask:0xf
	v_cndmask_b32_e64 v35, v40, v34, s[40:41]
	v_cndmask_b32_e64 v34, v34, v41, s[40:41]
	v_cvt_pk_bf16_f32 v35, v35, v34
	v_cndmask_b32_e64 v34, v42, v43, s[38:39]
	ds_write_b32 v152, v35 offset:50496
	s_nop 0
	v_mov_b32_dpp v34, v34 quad_perm:[1,0,3,2] row_mask:0xf bank_mask:0xf
	v_cndmask_b32_e64 v35, v42, v34, s[40:41]
	v_cndmask_b32_e64 v34, v34, v43, s[40:41]
	v_cvt_pk_bf16_f32 v35, v35, v34
	v_cndmask_b32_e64 v34, v44, v45, s[38:39]
	ds_write_b32 v152, v35 offset:51264
	s_nop 0
	v_mov_b32_dpp v34, v34 quad_perm:[1,0,3,2] row_mask:0xf bank_mask:0xf
	v_cndmask_b32_e64 v35, v44, v34, s[40:41]
	v_cndmask_b32_e64 v34, v34, v45, s[40:41]
	v_cvt_pk_bf16_f32 v35, v35, v34
	v_cndmask_b32_e64 v34, v46, v47, s[38:39]
	ds_write_b32 v152, v35 offset:51520
	s_nop 0
	v_mov_b32_dpp v34, v34 quad_perm:[1,0,3,2] row_mask:0xf bank_mask:0xf
	v_cndmask_b32_e64 v35, v46, v34, s[40:41]
	v_cndmask_b32_e64 v34, v34, v47, s[40:41]
	v_cvt_pk_bf16_f32 v35, v35, v34
	v_cndmask_b32_e64 v34, v48, v49, s[38:39]
	ds_write_b32 v152, v35 offset:52288
	s_nop 0
	v_mov_b32_dpp v34, v34 quad_perm:[1,0,3,2] row_mask:0xf bank_mask:0xf
	v_cndmask_b32_e64 v50, v48, v34, s[40:41]
	v_cndmask_b32_e64 v34, v34, v49, s[40:41]
	v_cvt_pk_bf16_f32 v50, v50, v34
	s_ashr_i32 s16, s34, 31
	s_lshr_b32 s16, s16, 28
	s_add_i32 s16, s34, s16
	s_ashr_i32 s16, s16, 4
	s_lshl_b32 s17, s16, s1
	s_add_i32 s17, s17, s0
	v_lshl_add_u32 v48, s17, 8, v134
	s_lshl_b32 s16, s16, 11
	ds_read_b128 v[36:39], v153 offset:49152
	ds_read_b128 v[40:43], v154 offset:49152
	s_sub_i32 s16, s23, s16
	v_or_b32_e32 v34, v48, v135
	s_ashr_i32 s17, s16, 31
	v_ashrrev_i32_e32 v35, 31, v34
	v_lshl_add_u64 v[46:47], s[16:17], 1, v[122:123]
	v_lshlrev_b64 v[34:35], 12, v[34:35]
	v_lshl_add_u64 v[34:35], v[46:47], 0, v[34:35]
	s_waitcnt lgkmcnt(1)
; DEVI unsigned cvtpk(float lo, float hi) { unsigned r; asm("v_cvt_pk_bf16_f32 %0, %1, %2" : "=v"(r) : "v"(lo), "v"(hi)); return r; }
; DEVI int crow(int r, int hi) { return (r & 3) + 8 * (r >> 2) + 4 * hi; }
; DEVI float xor1(float v) { return dppf<0xB1, 0xF>(v, v); }
; template <class RowPtr> DEVI void store2_bf16(const f32x16& a0, const f32x16& a1, char* slice, int lane, int col0, RowPtr rowptr) {
;   const int r32 = lane & 31, hi = lane >> 5; const bool odd = r32 & 1;
; #pragma unroll
;   for (int jj = 0; jj < 2; ++jj) {
; #pragma unroll
;     for (int r = 0; r < 16; r += 2) {
;       const float x0 = jj ? a1[r] : a0[r], x1 = jj ? a1[r + 1] : a0[r + 1];
;       const float send = odd ? x0 : x1;
;       const float recv = xor1(send);
;       const unsigned pk = odd ? cvtpk(recv, x1) : cvtpk(x0, recv);
;       const int rr = crow(odd ? r + 1 : r, hi);
;       *(unsigned*)(slice + rr * 128 + (jj * 32 + (r32 & ~1)) * 2) = pk;
;     }
;   }
; #pragma unroll
;   for (int ps = 0; ps < 4; ++ps) {
;     const int row = ps * 8 + (lane >> 3), ch = lane & 7;
;     const u32x4 v = *(const u32x4*)(slice + row * 128 + ch * 16);
;     *(u32x4*)(rowptr(row) + col0 + ch * 8) = v;
;   }
	global_store_dwordx4 v[34:35], v[36:39], off
	ds_write_b32 v152, v50 offset:52544
	s_nop 0
	v_or_b32_e32 v36, v48, v136
	v_ashrrev_i32_e32 v37, 31, v36
	v_lshlrev_b64 v[36:37], 12, v[36:37]
	v_lshl_add_u64 v[38:39], v[46:47], 0, v[36:37]
	s_waitcnt lgkmcnt(1)
	global_store_dwordx4 v[38:39], v[40:43], off
	ds_read_b128 v[42:45], v155 offset:49152
	v_or_b32_e32 v36, v48, v137
	v_ashrrev_i32_e32 v37, 31, v36
	v_lshlrev_b64 v[36:37], 12, v[36:37]
	v_lshl_add_u64 v[40:41], v[46:47], 0, v[36:37]
	s_waitcnt lgkmcnt(0)
	global_store_dwordx4 v[40:41], v[42:45], off
	ds_read_b128 v[42:45], v156 offset:49152
	v_or_b32_e32 v36, v48, v138
	v_ashrrev_i32_e32 v37, 31, v36
	v_lshlrev_b64 v[36:37], 12, v[36:37]
	v_lshl_add_u64 v[36:37], v[46:47], 0, v[36:37]
	s_waitcnt lgkmcnt(0)
	global_store_dwordx4 v[36:37], v[42:45], off
	s_nop 1
	v_cndmask_b32_e64 v42, v18, v19, s[38:39]
	s_nop 1
	v_mov_b32_dpp v42, v42 quad_perm:[1,0,3,2] row_mask:0xf bank_mask:0xf
	v_cndmask_b32_e64 v43, v18, v42, s[40:41]
	v_cndmask_b32_e64 v42, v42, v19, s[40:41]
	v_cvt_pk_bf16_f32 v43, v43, v42
	v_cndmask_b32_e64 v18, v20, v21, s[38:39]
	ds_write_b32 v152, v43 offset:49152
	s_nop 0
	v_mov_b32_dpp v18, v18 quad_perm:[1,0,3,2] row_mask:0xf bank_mask:0xf
	v_cndmask_b32_e64 v19, v20, v18, s[40:41]
	v_cndmask_b32_e64 v18, v18, v21, s[40:41]
	v_cvt_pk_bf16_f32 v19, v19, v18
	v_cndmask_b32_e64 v18, v22, v23, s[38:39]
	ds_write_b32 v152, v19 offset:49408
	s_nop 0
	v_mov_b32_dpp v18, v18 quad_perm:[1,0,3,2] row_mask:0xf bank_mask:0xf
	v_cndmask_b32_e64 v19, v22, v18, s[40:41]
	v_cndmask_b32_e64 v18, v18, v23, s[40:41]
	v_cvt_pk_bf16_f32 v19, v19, v18
	v_cndmask_b32_e64 v18, v24, v25, s[38:39]
	ds_write_b32 v152, v19 offset:50176
	s_nop 0
	v_mov_b32_dpp v18, v18 quad_perm:[1,0,3,2] row_mask:0xf bank_mask:0xf
	v_cndmask_b32_e64 v19, v24, v18, s[40:41]
	v_cndmask_b32_e64 v18, v18, v25, s[40:41]
	v_cvt_pk_bf16_f32 v19, v19, v18
	v_cndmask_b32_e64 v18, v26, v27, s[38:39]
	ds_write_b32 v152, v19 offset:50432
	s_nop 0
	v_mov_b32_dpp v18, v18 quad_perm:[1,0,3,2] row_mask:0xf bank_mask:0xf
	v_cndmask_b32_e64 v19, v26, v18, s[40:41]
	v_cndmask_b32_e64 v18, v18, v27, s[40:41]
	v_cvt_pk_bf16_f32 v19, v19, v18
	v_cndmask_b32_e64 v18, v28, v29, s[38:39]
	ds_write_b32 v152, v19 offset:51200
	s_nop 0
	v_mov_b32_dpp v18, v18 quad_perm:[1,0,3,2] row_mask:0xf bank_mask:0xf
	v_cndmask_b32_e64 v19, v28, v18, s[40:41]
	v_cndmask_b32_e64 v18, v18, v29, s[40:41]
	v_cvt_pk_bf16_f32 v19, v19, v18
	v_cndmask_b32_e64 v18, v30, v31, s[38:39]
	ds_write_b32 v152, v19 offset:51456
	s_nop 0
	v_mov_b32_dpp v18, v18 quad_perm:[1,0,3,2] row_mask:0xf bank_mask:0xf
	v_cndmask_b32_e64 v19, v30, v18, s[40:41]
	v_cndmask_b32_e64 v18, v18, v31, s[40:41]
	v_cvt_pk_bf16_f32 v19, v19, v18
	v_cndmask_b32_e64 v18, v32, v33, s[38:39]
	ds_write_b32 v152, v19 offset:52224
	s_nop 0
	v_mov_b32_dpp v18, v18 quad_perm:[1,0,3,2] row_mask:0xf bank_mask:0xf
	v_cndmask_b32_e64 v42, v32, v18, s[40:41]
	v_cndmask_b32_e64 v18, v18, v33, s[40:41]
	v_cvt_pk_bf16_f32 v42, v42, v18
	v_cndmask_b32_e64 v18, v2, v3, s[38:39]
	ds_write_b32 v152, v42 offset:52480
	s_nop 0
	v_mov_b32_dpp v18, v18 quad_perm:[1,0,3,2] row_mask:0xf bank_mask:0xf
	v_cndmask_b32_e64 v19, v2, v18, s[40:41]
	v_cndmask_b32_e64 v18, v18, v3, s[40:41]
	v_cvt_pk_bf16_f32 v19, v19, v18
	v_cndmask_b32_e64 v2, v4, v5, s[38:39]
	ds_write_b32 v152, v19 offset:49216
	s_nop 0
	v_mov_b32_dpp v2, v2 quad_perm:[1,0,3,2] row_mask:0xf bank_mask:0xf
	v_cndmask_b32_e64 v3, v4, v2, s[40:41]
	v_cndmask_b32_e64 v2, v2, v5, s[40:41]
	v_cvt_pk_bf16_f32 v3, v3, v2
	v_cndmask_b32_e64 v2, v6, v7, s[38:39]
	ds_write_b32 v152, v3 offset:49472
	s_nop 0
	v_mov_b32_dpp v2, v2 quad_perm:[1,0,3,2] row_mask:0xf bank_mask:0xf
	v_cndmask_b32_e64 v3, v6, v2, s[40:41]
	v_cndmask_b32_e64 v2, v2, v7, s[40:41]
	v_cvt_pk_bf16_f32 v3, v3, v2
	v_cndmask_b32_e64 v2, v8, v9, s[38:39]
	ds_write_b32 v152, v3 offset:50240
	s_nop 0
	v_mov_b32_dpp v2, v2 quad_perm:[1,0,3,2] row_mask:0xf bank_mask:0xf
	v_cndmask_b32_e64 v3, v8, v2, s[40:41]
	v_cndmask_b32_e64 v2, v2, v9, s[40:41]
	v_cvt_pk_bf16_f32 v3, v3, v2
	v_cndmask_b32_e64 v2, v10, v11, s[38:39]
	ds_write_b32 v152, v3 offset:50496
	s_nop 0
	v_mov_b32_dpp v2, v2 quad_perm:[1,0,3,2] row_mask:0xf bank_mask:0xf
	v_cndmask_b32_e64 v3, v10, v2, s[40:41]
	v_cndmask_b32_e64 v2, v2, v11, s[40:41]
	v_cvt_pk_bf16_f32 v3, v3, v2
	v_cndmask_b32_e64 v2, v12, v13, s[38:39]
	ds_write_b32 v152, v3 offset:51264
	s_nop 0
	v_mov_b32_dpp v2, v2 quad_perm:[1,0,3,2] row_mask:0xf bank_mask:0xf
	v_cndmask_b32_e64 v3, v12, v2, s[40:41]
	v_cndmask_b32_e64 v2, v2, v13, s[40:41]
	v_cvt_pk_bf16_f32 v3, v3, v2
	v_cndmask_b32_e64 v2, v14, v15, s[38:39]
	ds_write_b32 v152, v3 offset:51520
	s_nop 0
	v_mov_b32_dpp v2, v2 quad_perm:[1,0,3,2] row_mask:0xf bank_mask:0xf
	v_cndmask_b32_e64 v3, v14, v2, s[40:41]
	v_cndmask_b32_e64 v2, v2, v15, s[40:41]
	v_cvt_pk_bf16_f32 v3, v3, v2
	v_cndmask_b32_e64 v2, v16, v17, s[38:39]
	ds_write_b32 v152, v3 offset:52288
	s_nop 0
	v_mov_b32_dpp v2, v2 quad_perm:[1,0,3,2] row_mask:0xf bank_mask:0xf
	s_and_saveexec_b64 s[16:17], s[40:41]
	s_xor_b64 s[16:17], exec, s[16:17]
	s_cbranch_execz .LBB0_346
	v_cvt_pk_bf16_f32 v18, v2, v17

; DEVI unsigned cvtpk(float lo, float hi) { unsigned r; asm("v_cvt_pk_bf16_f32 %0, %1, %2" : "=v"(r) : "v"(lo), "v"(hi)); return r; }
; DEVI int crow(int r, int hi) { return (r & 3) + 8 * (r >> 2) + 4 * hi; }
; DEVI float xor1(float v) { return dppf<0xB1, 0xF>(v, v); }
; template <class RowPtr> DEVI void store2_bf16(const f32x16& a0, const f32x16& a1, char* slice, int lane, int col0, RowPtr rowptr) {
;   const int r32 = lane & 31, hi = lane >> 5; const bool odd = r32 & 1;
; #pragma unroll
;   for (int jj = 0; jj < 2; ++jj) {
; #pragma unroll
;     for (int r = 0; r < 16; r += 2) {
;       const float x0 = jj ? a1[r] : a0[r], x1 = jj ? a1[r + 1] : a0[r + 1];
;       const float send = odd ? x0 : x1;
;       const float recv = xor1(send);
;       const unsigned pk = odd ? cvtpk(recv, x1) : cvtpk(x0, recv);
;       const int rr = crow(odd ? r + 1 : r, hi);
;       *(unsigned*)(slice + rr * 128 + (jj * 32 + (r32 & ~1)) * 2) = pk;
;     }
;   }
; #pragma unroll
;   for (int ps = 0; ps < 4; ++ps) {
;     const int row = ps * 8 + (lane >> 3), ch = lane & 7;
;     const u32x4 v = *(const u32x4*)(slice + row * 128 + ch * 16);
;     *(u32x4*)(rowptr(row) + col0 + ch * 8) = v;
;   }
.LBB0_1328:
	v_cndmask_b32_e64 v124, v50, v51, s[38:39]
	s_nop 1
	v_mov_b32_dpp v124, v124 quad_perm:[1,0,3,2] row_mask:0xf bank_mask:0xf
	v_cndmask_b32_e64 v125, v50, v124, s[40:41]
	v_cndmask_b32_e64 v124, v124, v51, s[40:41]
	v_cvt_pk_bf16_f32 v125, v125, v124
	v_cndmask_b32_e64 v50, v52, v53, s[38:39]
	ds_write_b32 v152, v125 offset:49152
	s_nop 0
	v_mov_b32_dpp v50, v50 quad_perm:[1,0,3,2] row_mask:0xf bank_mask:0xf
	v_cndmask_b32_e64 v51, v52, v50, s[40:41]
	v_cndmask_b32_e64 v50, v50, v53, s[40:41]
	v_cvt_pk_bf16_f32 v51, v51, v50
	v_cndmask_b32_e64 v50, v54, v55, s[38:39]
	ds_write_b32 v152, v51 offset:49408
	s_nop 0
	v_mov_b32_dpp v50, v50 quad_perm:[1,0,3,2] row_mask:0xf bank_mask:0xf
	v_cndmask_b32_e64 v51, v54, v50, s[40:41]
	v_cndmask_b32_e64 v50, v50, v55, s[40:41]
	v_cvt_pk_bf16_f32 v51, v51, v50
	v_cndmask_b32_e64 v50, v56, v57, s[38:39]
	ds_write_b32 v152, v51 offset:50176
	s_nop 0
	v_mov_b32_dpp v50, v50 quad_perm:[1,0,3,2] row_mask:0xf bank_mask:0xf
	v_cndmask_b32_e64 v51, v56, v50, s[40:41]
	v_cndmask_b32_e64 v50, v50, v57, s[40:41]
	v_cvt_pk_bf16_f32 v51, v51, v50
	v_cndmask_b32_e64 v50, v58, v59, s[38:39]
	ds_write_b32 v152, v51 offset:50432
	s_nop 0
	v_mov_b32_dpp v50, v50 quad_perm:[1,0,3,2] row_mask:0xf bank_mask:0xf
	v_cndmask_b32_e64 v51, v58, v50, s[40:41]
	v_cndmask_b32_e64 v50, v50, v59, s[40:41]
	v_cvt_pk_bf16_f32 v51, v51, v50
	v_cndmask_b32_e64 v50, v60, v61, s[38:39]
	ds_write_b32 v152, v51 offset:51200
	s_nop 0
	v_mov_b32_dpp v50, v50 quad_perm:[1,0,3,2] row_mask:0xf bank_mask:0xf
	v_cndmask_b32_e64 v51, v60, v50, s[40:41]
	v_cndmask_b32_e64 v50, v50, v61, s[40:41]
	v_cvt_pk_bf16_f32 v51, v51, v50
	v_cndmask_b32_e64 v50, v62, v63, s[38:39]
	ds_write_b32 v152, v51 offset:51456
	s_nop 0
	v_mov_b32_dpp v50, v50 quad_perm:[1,0,3,2] row_mask:0xf bank_mask:0xf
	v_cndmask_b32_e64 v51, v62, v50, s[40:41]
	v_cndmask_b32_e64 v50, v50, v63, s[40:41]
	v_cvt_pk_bf16_f32 v51, v51, v50
	v_cndmask_b32_e64 v50, v64, v65, s[38:39]
	ds_write_b32 v152, v51 offset:52224
	s_nop 0
	v_mov_b32_dpp v50, v50 quad_perm:[1,0,3,2] row_mask:0xf bank_mask:0xf
	v_cndmask_b32_e64 v124, v64, v50, s[40:41]
	v_cndmask_b32_e64 v50, v50, v65, s[40:41]
	v_cvt_pk_bf16_f32 v124, v124, v50
	v_cndmask_b32_e64 v50, v34, v35, s[38:39]
	ds_write_b32 v152, v124 offset:52480
	s_nop 0
	v_mov_b32_dpp v50, v50 quad_perm:[1,0,3,2] row_mask:0xf bank_mask:0xf
	v_cndmask_b32_e64 v51, v34, v50, s[40:41]
	v_cndmask_b32_e64 v50, v50, v35, s[40:41]
	v_cvt_pk_bf16_f32 v51, v51, v50
	v_cndmask_b32_e64 v34, v36, v37, s[38:39]
	ds_write_b32 v152, v51 offset:49216
	s_nop 0
	v_mov_b32_dpp v34, v34 quad_perm:[1,0,3,2] row_mask:0xf bank_mask:0xf
	v_cndmask_b32_e64 v35, v36, v34, s[40:41]
	v_cndmask_b32_e64 v34, v34, v37, s[40:41]
	v_cvt_pk_bf16_f32 v35, v35, v34
	v_cndmask_b32_e64 v34, v38, v39, s[38:39]
	ds_write_b32 v152, v35 offset:49472
	s_nop 0
	v_mov_b32_dpp v34, v34 quad_perm:[1,0,3,2] row_mask:0xf bank_mask:0xf
	v_cndmask_b32_e64 v35, v38, v34, s[40:41]
	v_cndmask_b32_e64 v34, v34, v39, s[40:41]
	v_cvt_pk_bf16_f32 v35, v35, v34
	v_cndmask_b32_e64 v34, v40, v41, s[38:39]
	ds_write_b32 v152, v35 offset:50240
	s_nop 0
	v_mov_b32_dpp v34, v34 quad_perm:[1,0,3,2] row_mask:0xf bank_mask:0xf
	v_cndmask_b32_e64 v35, v40, v34, s[40:41]
	v_cndmask_b32_e64 v34, v34, v41, s[40:41]
	v_cvt_pk_bf16_f32 v35, v35, v34
	v_cndmask_b32_e64 v34, v42, v43, s[38:39]
	ds_write_b32 v152, v35 offset:50496
	s_nop 0
	v_mov_b32_dpp v34, v34 quad_perm:[1,0,3,2] row_mask:0xf bank_mask:0xf
	v_cndmask_b32_e64 v35, v42, v34, s[40:41]
	v_cndmask_b32_e64 v34, v34, v43, s[40:41]
	v_cvt_pk_bf16_f32 v35, v35, v34
	v_cndmask_b32_e64 v34, v44, v45, s[38:39]
	ds_write_b32 v152, v35 offset:51264
	s_nop 0
	v_mov_b32_dpp v34, v34 quad_perm:[1,0,3,2] row_mask:0xf bank_mask:0xf
	v_cndmask_b32_e64 v35, v44, v34, s[40:41]
	v_cndmask_b32_e64 v34, v34, v45, s[40:41]
	v_cvt_pk_bf16_f32 v35, v35, v34
	v_cndmask_b32_e64 v34, v46, v47, s[38:39]
	ds_write_b32 v152, v35 offset:51520
	s_nop 0
	v_mov_b32_dpp v34, v34 quad_perm:[1,0,3,2] row_mask:0xf bank_mask:0xf
	v_cndmask_b32_e64 v35, v46, v34, s[40:41]
	v_cndmask_b32_e64 v34, v34, v47, s[40:41]
	v_cvt_pk_bf16_f32 v35, v35, v34
	v_cndmask_b32_e64 v34, v48, v49, s[38:39]
	ds_write_b32 v152, v35 offset:52288
	s_nop 0
	v_mov_b32_dpp v34, v34 quad_perm:[1,0,3,2] row_mask:0xf bank_mask:0xf
	v_cndmask_b32_e64 v50, v48, v34, s[40:41]
	v_cndmask_b32_e64 v34, v34, v49, s[40:41]
	v_cvt_pk_bf16_f32 v50, v50, v34
	s_ashr_i32 s12, s22, 31
	s_lshr_b32 s12, s12, 28
	s_add_i32 s12, s22, s12
	s_ashr_i32 s12, s12, 4
	s_lshl_b32 s13, s12, s1
	s_add_i32 s13, s13, s0
	v_lshl_add_u32 v48, s13, 8, v134
	s_lshl_b32 s12, s12, 11
	ds_read_b128 v[36:39], v153 offset:49152
	ds_read_b128 v[40:43], v154 offset:49152
	s_sub_i32 s12, s15, s12
	v_or_b32_e32 v34, v48, v135
	s_ashr_i32 s13, s12, 31
	v_ashrrev_i32_e32 v35, 31, v34
	v_lshl_add_u64 v[46:47], s[12:13], 1, v[122:123]
	v_lshlrev_b64 v[34:35], 12, v[34:35]
	v_lshl_add_u64 v[34:35], v[46:47], 0, v[34:35]
	s_waitcnt lgkmcnt(1)
; DEVI unsigned cvtpk(float lo, float hi) { unsigned r; asm("v_cvt_pk_bf16_f32 %0, %1, %2" : "=v"(r) : "v"(lo), "v"(hi)); return r; }
; DEVI int crow(int r, int hi) { return (r & 3) + 8 * (r >> 2) + 4 * hi; }
; DEVI float xor1(float v) { return dppf<0xB1, 0xF>(v, v); }
; template <class RowPtr> DEVI void store2_bf16(const f32x16& a0, const f32x16& a1, char* slice, int lane, int col0, RowPtr rowptr) {
;   const int r32 = lane & 31, hi = lane >> 5; const bool odd = r32 & 1;
; #pragma unroll
;   for (int jj = 0; jj < 2; ++jj) {
; #pragma unroll
;     for (int r = 0; r < 16; r += 2) {
;       const float x0 = jj ? a1[r] : a0[r], x1 = jj ? a1[r + 1] : a0[r + 1];
;       const float send = odd ? x0 : x1;
;       const float recv = xor1(send);
;       const unsigned pk = odd ? cvtpk(recv, x1) : cvtpk(x0, recv);
;       const int rr = crow(odd ? r + 1 : r, hi);
;       *(unsigned*)(slice + rr * 128 + (jj * 32 + (r32 & ~1)) * 2) = pk;
;     }
;   }
; #pragma unroll
;   for (int ps = 0; ps < 4; ++ps) {
;     const int row = ps * 8 + (lane >> 3), ch = lane & 7;
;     const u32x4 v = *(const u32x4*)(slice + row * 128 + ch * 16);
;     *(u32x4*)(rowptr(row) + col0 + ch * 8) = v;
;   }
	global_store_dwordx4 v[34:35], v[36:39], off
	ds_write_b32 v152, v50 offset:52544
	s_nop 0
	v_or_b32_e32 v36, v48, v136
	v_ashrrev_i32_e32 v37, 31, v36
	v_lshlrev_b64 v[36:37], 12, v[36:37]
	v_lshl_add_u64 v[38:39], v[46:47], 0, v[36:37]
	s_waitcnt lgkmcnt(1)
	global_store_dwordx4 v[38:39], v[40:43], off
	ds_read_b128 v[42:45], v155 offset:49152
	v_or_b32_e32 v36, v48, v137
	v_ashrrev_i32_e32 v37, 31, v36
	v_lshlrev_b64 v[36:37], 12, v[36:37]
	v_lshl_add_u64 v[40:41], v[46:47], 0, v[36:37]
	s_waitcnt lgkmcnt(0)
	global_store_dwordx4 v[40:41], v[42:45], off
	ds_read_b128 v[42:45], v156 offset:49152
	v_or_b32_e32 v36, v48, v138
	v_ashrrev_i32_e32 v37, 31, v36
	v_lshlrev_b64 v[36:37], 12, v[36:37]
	v_lshl_add_u64 v[36:37], v[46:47], 0, v[36:37]
	s_waitcnt lgkmcnt(0)
	global_store_dwordx4 v[36:37], v[42:45], off
	s_nop 1
	v_cndmask_b32_e64 v42, v18, v19, s[38:39]
	s_nop 1
	v_mov_b32_dpp v42, v42 quad_perm:[1,0,3,2] row_mask:0xf bank_mask:0xf
	v_cndmask_b32_e64 v43, v18, v42, s[40:41]
	v_cndmask_b32_e64 v42, v42, v19, s[40:41]
	v_cvt_pk_bf16_f32 v43, v43, v42
	v_cndmask_b32_e64 v18, v20, v21, s[38:39]
	ds_write_b32 v152, v43 offset:49152
	s_nop 0
	v_mov_b32_dpp v18, v18 quad_perm:[1,0,3,2] row_mask:0xf bank_mask:0xf
	v_cndmask_b32_e64 v19, v20, v18, s[40:41]
	v_cndmask_b32_e64 v18, v18, v21, s[40:41]
	v_cvt_pk_bf16_f32 v19, v19, v18
	v_cndmask_b32_e64 v18, v22, v23, s[38:39]
	ds_write_b32 v152, v19 offset:49408
	s_nop 0
	v_mov_b32_dpp v18, v18 quad_perm:[1,0,3,2] row_mask:0xf bank_mask:0xf
	v_cndmask_b32_e64 v19, v22, v18, s[40:41]
	v_cndmask_b32_e64 v18, v18, v23, s[40:41]
	v_cvt_pk_bf16_f32 v19, v19, v18
	v_cndmask_b32_e64 v18, v24, v25, s[38:39]
	ds_write_b32 v152, v19 offset:50176
	s_nop 0
	v_mov_b32_dpp v18, v18 quad_perm:[1,0,3,2] row_mask:0xf bank_mask:0xf
	v_cndmask_b32_e64 v19, v24, v18, s[40:41]
	v_cndmask_b32_e64 v18, v18, v25, s[40:41]
	v_cvt_pk_bf16_f32 v19, v19, v18
	v_cndmask_b32_e64 v18, v26, v27, s[38:39]
	ds_write_b32 v152, v19 offset:50432
	s_nop 0
	v_mov_b32_dpp v18, v18 quad_perm:[1,0,3,2] row_mask:0xf bank_mask:0xf
	v_cndmask_b32_e64 v19, v26, v18, s[40:41]
	v_cndmask_b32_e64 v18, v18, v27, s[40:41]
	v_cvt_pk_bf16_f32 v19, v19, v18
	v_cndmask_b32_e64 v18, v28, v29, s[38:39]
	ds_write_b32 v152, v19 offset:51200
	s_nop 0
	v_mov_b32_dpp v18, v18 quad_perm:[1,0,3,2] row_mask:0xf bank_mask:0xf
	v_cndmask_b32_e64 v19, v28, v18, s[40:41]
	v_cndmask_b32_e64 v18, v18, v29, s[40:41]
	v_cvt_pk_bf16_f32 v19, v19, v18
	v_cndmask_b32_e64 v18, v30, v31, s[38:39]
	ds_write_b32 v152, v19 offset:51456
	s_nop 0
	v_mov_b32_dpp v18, v18 quad_perm:[1,0,3,2] row_mask:0xf bank_mask:0xf
	v_cndmask_b32_e64 v19, v30, v18, s[40:41]
	v_cndmask_b32_e64 v18, v18, v31, s[40:41]
	v_cvt_pk_bf16_f32 v19, v19, v18
	v_cndmask_b32_e64 v18, v32, v33, s[38:39]
	ds_write_b32 v152, v19 offset:52224
	s_nop 0
	v_mov_b32_dpp v18, v18 quad_perm:[1,0,3,2] row_mask:0xf bank_mask:0xf
	v_cndmask_b32_e64 v42, v32, v18, s[40:41]
	v_cndmask_b32_e64 v18, v18, v33, s[40:41]
	v_cvt_pk_bf16_f32 v42, v42, v18
	v_cndmask_b32_e64 v18, v2, v3, s[38:39]
	ds_write_b32 v152, v42 offset:52480
	s_nop 0
	v_mov_b32_dpp v18, v18 quad_perm:[1,0,3,2] row_mask:0xf bank_mask:0xf
	v_cndmask_b32_e64 v19, v2, v18, s[40:41]
	v_cndmask_b32_e64 v18, v18, v3, s[40:41]
	v_cvt_pk_bf16_f32 v19, v19, v18
	v_cndmask_b32_e64 v2, v4, v5, s[38:39]
	ds_write_b32 v152, v19 offset:49216
	s_nop 0
	v_mov_b32_dpp v2, v2 quad_perm:[1,0,3,2] row_mask:0xf bank_mask:0xf
	v_cndmask_b32_e64 v3, v4, v2, s[40:41]
	v_cndmask_b32_e64 v2, v2, v5, s[40:41]
	v_cvt_pk_bf16_f32 v3, v3, v2
	v_cndmask_b32_e64 v2, v6, v7, s[38:39]
	ds_write_b32 v152, v3 offset:49472
	s_nop 0
	v_mov_b32_dpp v2, v2 quad_perm:[1,0,3,2] row_mask:0xf bank_mask:0xf
	v_cndmask_b32_e64 v3, v6, v2, s[40:41]
	v_cndmask_b32_e64 v2, v2, v7, s[40:41]
	v_cvt_pk_bf16_f32 v3, v3, v2
	v_cndmask_b32_e64 v2, v8, v9, s[38:39]
	ds_write_b32 v152, v3 offset:50240
	s_nop 0
	v_mov_b32_dpp v2, v2 quad_perm:[1,0,3,2] row_mask:0xf bank_mask:0xf
	v_cndmask_b32_e64 v3, v8, v2, s[40:41]
	v_cndmask_b32_e64 v2, v2, v9, s[40:41]
	v_cvt_pk_bf16_f32 v3, v3, v2
	v_cndmask_b32_e64 v2, v10, v11, s[38:39]
	ds_write_b32 v152, v3 offset:50496
	s_nop 0
	v_mov_b32_dpp v2, v2 quad_perm:[1,0,3,2] row_mask:0xf bank_mask:0xf
	v_cndmask_b32_e64 v3, v10, v2, s[40:41]
	v_cndmask_b32_e64 v2, v2, v11, s[40:41]
	v_cvt_pk_bf16_f32 v3, v3, v2
	v_cndmask_b32_e64 v2, v12, v13, s[38:39]
	ds_write_b32 v152, v3 offset:51264
	s_nop 0
	v_mov_b32_dpp v2, v2 quad_perm:[1,0,3,2] row_mask:0xf bank_mask:0xf
	v_cndmask_b32_e64 v3, v12, v2, s[40:41]
	v_cndmask_b32_e64 v2, v2, v13, s[40:41]
	v_cvt_pk_bf16_f32 v3, v3, v2
	v_cndmask_b32_e64 v2, v14, v15, s[38:39]
	ds_write_b32 v152, v3 offset:51520
	s_nop 0
	v_mov_b32_dpp v2, v2 quad_perm:[1,0,3,2] row_mask:0xf bank_mask:0xf
	v_cndmask_b32_e64 v3, v14, v2, s[40:41]
	v_cndmask_b32_e64 v2, v2, v15, s[40:41]
	v_cvt_pk_bf16_f32 v3, v3, v2
	v_cndmask_b32_e64 v2, v16, v17, s[38:39]
	ds_write_b32 v152, v3 offset:52288
	s_nop 0
	v_mov_b32_dpp v2, v2 quad_perm:[1,0,3,2] row_mask:0xf bank_mask:0xf
	s_and_saveexec_b64 s[12:13], s[40:41]
	s_xor_b64 s[12:13], exec, s[12:13]
	s_cbranch_execz .LBB0_1454
	v_cvt_pk_bf16_f32 v18, v2, v17

; DEVI unsigned cvtpk(float lo, float hi) { unsigned r; asm("v_cvt_pk_bf16_f32 %0, %1, %2" : "=v"(r) : "v"(lo), "v"(hi)); return r; }
; DEVI int crow(int r, int hi) { return (r & 3) + 8 * (r >> 2) + 4 * hi; }
; DEVI float xor1(float v) { return dppf<0xB1, 0xF>(v, v); }
; template <class RowPtr> DEVI void store2_bf16(const f32x16& a0, const f32x16& a1, char* slice, int lane, int col0, RowPtr rowptr) {
;   const int r32 = lane & 31, hi = lane >> 5; const bool odd = r32 & 1;
; #pragma unroll
;   for (int jj = 0; jj < 2; ++jj) {
; #pragma unroll
;     for (int r = 0; r < 16; r += 2) {
;       const float x0 = jj ? a1[r] : a0[r], x1 = jj ? a1[r + 1] : a0[r + 1];
;       const float send = odd ? x0 : x1;
;       const float recv = xor1(send);
;       const unsigned pk = odd ? cvtpk(recv, x1) : cvtpk(x0, recv);
;       const int rr = crow(odd ? r + 1 : r, hi);
;       *(unsigned*)(slice + rr * 128 + (jj * 32 + (r32 & ~1)) * 2) = pk;
;     }
;   }
; #pragma unroll
;   for (int ps = 0; ps < 4; ++ps) {
;     const int row = ps * 8 + (lane >> 3), ch = lane & 7;
;     const u32x4 v = *(const u32x4*)(slice + row * 128 + ch * 16);
;     *(u32x4*)(rowptr(row) + col0 + ch * 8) = v;
;   }
; }
.LBB0_2144:
	v_cndmask_b32_e64 v124, v50, v51, s[38:39]
	s_nop 1
	v_mov_b32_dpp v124, v124 quad_perm:[1,0,3,2] row_mask:0xf bank_mask:0xf
	v_cndmask_b32_e64 v125, v50, v124, s[40:41]
	v_cndmask_b32_e64 v124, v124, v51, s[40:41]
	v_cvt_pk_bf16_f32 v125, v125, v124
	v_cndmask_b32_e64 v50, v52, v53, s[38:39]
	ds_write_b32 v152, v125 offset:49152
	s_nop 0
	v_mov_b32_dpp v50, v50 quad_perm:[1,0,3,2] row_mask:0xf bank_mask:0xf
	v_cndmask_b32_e64 v51, v52, v50, s[40:41]
	v_cndmask_b32_e64 v50, v50, v53, s[40:41]
	v_cvt_pk_bf16_f32 v51, v51, v50
	v_cndmask_b32_e64 v50, v54, v55, s[38:39]
	ds_write_b32 v152, v51 offset:49408
	s_nop 0
	v_mov_b32_dpp v50, v50 quad_perm:[1,0,3,2] row_mask:0xf bank_mask:0xf
	v_cndmask_b32_e64 v51, v54, v50, s[40:41]
	v_cndmask_b32_e64 v50, v50, v55, s[40:41]
	v_cvt_pk_bf16_f32 v51, v51, v50
	v_cndmask_b32_e64 v50, v56, v57, s[38:39]
	ds_write_b32 v152, v51 offset:50176
	s_nop 0
	v_mov_b32_dpp v50, v50 quad_perm:[1,0,3,2] row_mask:0xf bank_mask:0xf
	v_cndmask_b32_e64 v51, v56, v50, s[40:41]
	v_cndmask_b32_e64 v50, v50, v57, s[40:41]
	v_cvt_pk_bf16_f32 v51, v51, v50
	v_cndmask_b32_e64 v50, v58, v59, s[38:39]
	ds_write_b32 v152, v51 offset:50432
	s_nop 0
	v_mov_b32_dpp v50, v50 quad_perm:[1,0,3,2] row_mask:0xf bank_mask:0xf
	v_cndmask_b32_e64 v51, v58, v50, s[40:41]
	v_cndmask_b32_e64 v50, v50, v59, s[40:41]
	v_cvt_pk_bf16_f32 v51, v51, v50
	v_cndmask_b32_e64 v50, v60, v61, s[38:39]
	ds_write_b32 v152, v51 offset:51200
	s_nop 0
	v_mov_b32_dpp v50, v50 quad_perm:[1,0,3,2] row_mask:0xf bank_mask:0xf
	v_cndmask_b32_e64 v51, v60, v50, s[40:41]
	v_cndmask_b32_e64 v50, v50, v61, s[40:41]
	v_cvt_pk_bf16_f32 v51, v51, v50
	v_cndmask_b32_e64 v50, v62, v63, s[38:39]
	ds_write_b32 v152, v51 offset:51456
	s_nop 0
	v_mov_b32_dpp v50, v50 quad_perm:[1,0,3,2] row_mask:0xf bank_mask:0xf
	v_cndmask_b32_e64 v51, v62, v50, s[40:41]
	v_cndmask_b32_e64 v50, v50, v63, s[40:41]
	v_cvt_pk_bf16_f32 v51, v51, v50
	v_cndmask_b32_e64 v50, v64, v65, s[38:39]
	ds_write_b32 v152, v51 offset:52224
	s_nop 0
	v_mov_b32_dpp v50, v50 quad_perm:[1,0,3,2] row_mask:0xf bank_mask:0xf
	v_cndmask_b32_e64 v124, v64, v50, s[40:41]
	v_cndmask_b32_e64 v50, v50, v65, s[40:41]
	v_cvt_pk_bf16_f32 v124, v124, v50
	v_cndmask_b32_e64 v50, v34, v35, s[38:39]
	ds_write_b32 v152, v124 offset:52480
	s_nop 0
	v_mov_b32_dpp v50, v50 quad_perm:[1,0,3,2] row_mask:0xf bank_mask:0xf
	v_cndmask_b32_e64 v51, v34, v50, s[40:41]
	v_cndmask_b32_e64 v50, v50, v35, s[40:41]
	v_cvt_pk_bf16_f32 v51, v51, v50
	v_cndmask_b32_e64 v34, v36, v37, s[38:39]
	ds_write_b32 v152, v51 offset:49216
	s_nop 0
	v_mov_b32_dpp v34, v34 quad_perm:[1,0,3,2] row_mask:0xf bank_mask:0xf
	v_cndmask_b32_e64 v35, v36, v34, s[40:41]
	v_cndmask_b32_e64 v34, v34, v37, s[40:41]
	v_cvt_pk_bf16_f32 v35, v35, v34
	v_cndmask_b32_e64 v34, v38, v39, s[38:39]
	ds_write_b32 v152, v35 offset:49472
	s_nop 0
	v_mov_b32_dpp v34, v34 quad_perm:[1,0,3,2] row_mask:0xf bank_mask:0xf
	v_cndmask_b32_e64 v35, v38, v34, s[40:41]
	v_cndmask_b32_e64 v34, v34, v39, s[40:41]
	v_cvt_pk_bf16_f32 v35, v35, v34
	v_cndmask_b32_e64 v34, v40, v41, s[38:39]
	ds_write_b32 v152, v35 offset:50240
	s_nop 0
	v_mov_b32_dpp v34, v34 quad_perm:[1,0,3,2] row_mask:0xf bank_mask:0xf
	v_cndmask_b32_e64 v35, v40, v34, s[40:41]
	v_cndmask_b32_e64 v34, v34, v41, s[40:41]
	v_cvt_pk_bf16_f32 v35, v35, v34
	v_cndmask_b32_e64 v34, v42, v43, s[38:39]
	ds_write_b32 v152, v35 offset:50496
	s_nop 0
	v_mov_b32_dpp v34, v34 quad_perm:[1,0,3,2] row_mask:0xf bank_mask:0xf
	v_cndmask_b32_e64 v35, v42, v34, s[40:41]
	v_cndmask_b32_e64 v34, v34, v43, s[40:41]
	v_cvt_pk_bf16_f32 v35, v35, v34
	v_cndmask_b32_e64 v34, v44, v45, s[38:39]
	ds_write_b32 v152, v35 offset:51264
	s_nop 0
	v_mov_b32_dpp v34, v34 quad_perm:[1,0,3,2] row_mask:0xf bank_mask:0xf
	v_cndmask_b32_e64 v35, v44, v34, s[40:41]
	v_cndmask_b32_e64 v34, v34, v45, s[40:41]
	v_cvt_pk_bf16_f32 v35, v35, v34
	v_cndmask_b32_e64 v34, v46, v47, s[38:39]
	ds_write_b32 v152, v35 offset:51520
	s_nop 0
	v_mov_b32_dpp v34, v34 quad_perm:[1,0,3,2] row_mask:0xf bank_mask:0xf
	v_cndmask_b32_e64 v35, v46, v34, s[40:41]
	v_cndmask_b32_e64 v34, v34, v47, s[40:41]
	v_cvt_pk_bf16_f32 v35, v35, v34
	v_cndmask_b32_e64 v34, v48, v49, s[38:39]
	ds_write_b32 v152, v35 offset:52288
	s_nop 0
	v_mov_b32_dpp v34, v34 quad_perm:[1,0,3,2] row_mask:0xf bank_mask:0xf
	v_cndmask_b32_e64 v50, v48, v34, s[40:41]
	v_cndmask_b32_e64 v34, v34, v49, s[40:41]
	v_cvt_pk_bf16_f32 v50, v50, v34
	s_ashr_i32 s12, s22, 31
	s_lshr_b32 s12, s12, 30
	s_add_i32 s12, s22, s12
	s_ashr_i32 s12, s12, 2
	s_lshl_b32 s13, s12, s1
	s_add_i32 s13, s13, s0
	v_lshl_add_u32 v48, s13, 8, v134
	s_lshl_b32 s12, s12, 9
	ds_read_b128 v[36:39], v153 offset:49152
	ds_read_b128 v[40:43], v154 offset:49152
	s_sub_i32 s12, s15, s12
	v_or_b32_e32 v34, v48, v135
	s_ashr_i32 s13, s12, 31
	v_ashrrev_i32_e32 v35, 31, v34
	v_lshl_add_u64 v[46:47], s[12:13], 1, v[122:123]
	v_lshlrev_b64 v[34:35], 10, v[34:35]
	v_lshl_add_u64 v[34:35], v[46:47], 0, v[34:35]
	s_waitcnt lgkmcnt(1)
; DEVI unsigned cvtpk(float lo, float hi) { unsigned r; asm("v_cvt_pk_bf16_f32 %0, %1, %2" : "=v"(r) : "v"(lo), "v"(hi)); return r; }
; DEVI int crow(int r, int hi) { return (r & 3) + 8 * (r >> 2) + 4 * hi; }
; DEVI float xor1(float v) { return dppf<0xB1, 0xF>(v, v); }
; template <class RowPtr> DEVI void store2_bf16(const f32x16& a0, const f32x16& a1, char* slice, int lane, int col0, RowPtr rowptr) {
;   const int r32 = lane & 31, hi = lane >> 5; const bool odd = r32 & 1;
; #pragma unroll
;   for (int jj = 0; jj < 2; ++jj) {
; #pragma unroll
;     for (int r = 0; r < 16; r += 2) {
;       const float x0 = jj ? a1[r] : a0[r], x1 = jj ? a1[r + 1] : a0[r + 1];
;       const float send = odd ? x0 : x1;
;       const float recv = xor1(send);
;       const unsigned pk = odd ? cvtpk(recv, x1) : cvtpk(x0, recv);
;       const int rr = crow(odd ? r + 1 : r, hi);
;       *(unsigned*)(slice + rr * 128 + (jj * 32 + (r32 & ~1)) * 2) = pk;
;     }
;   }
; #pragma unroll
;   for (int ps = 0; ps < 4; ++ps) {
;     const int row = ps * 8 + (lane >> 3), ch = lane & 7;
;     const u32x4 v = *(const u32x4*)(slice + row * 128 + ch * 16);
;     *(u32x4*)(rowptr(row) + col0 + ch * 8) = v;
;   }
; }
	global_store_dwordx4 v[34:35], v[36:39], off
	ds_write_b32 v152, v50 offset:52544
	s_nop 0
	v_or_b32_e32 v36, v48, v136
	v_ashrrev_i32_e32 v37, 31, v36
	v_lshlrev_b64 v[36:37], 10, v[36:37]
	v_lshl_add_u64 v[38:39], v[46:47], 0, v[36:37]
	s_waitcnt lgkmcnt(1)
	global_store_dwordx4 v[38:39], v[40:43], off
	ds_read_b128 v[42:45], v155 offset:49152
	v_or_b32_e32 v36, v48, v137
	v_ashrrev_i32_e32 v37, 31, v36
	v_lshlrev_b64 v[36:37], 10, v[36:37]
	v_lshl_add_u64 v[40:41], v[46:47], 0, v[36:37]
	s_waitcnt lgkmcnt(0)
	global_store_dwordx4 v[40:41], v[42:45], off
	ds_read_b128 v[42:45], v156 offset:49152
	v_or_b32_e32 v36, v48, v138
	v_ashrrev_i32_e32 v37, 31, v36
	v_lshlrev_b64 v[36:37], 10, v[36:37]
	v_lshl_add_u64 v[36:37], v[46:47], 0, v[36:37]
	s_waitcnt lgkmcnt(0)
	global_store_dwordx4 v[36:37], v[42:45], off
	s_nop 1
	v_cndmask_b32_e64 v42, v18, v19, s[38:39]
	s_nop 1
	v_mov_b32_dpp v42, v42 quad_perm:[1,0,3,2] row_mask:0xf bank_mask:0xf
	v_cndmask_b32_e64 v43, v18, v42, s[40:41]
	v_cndmask_b32_e64 v42, v42, v19, s[40:41]
	v_cvt_pk_bf16_f32 v43, v43, v42
	v_cndmask_b32_e64 v18, v20, v21, s[38:39]
	ds_write_b32 v152, v43 offset:49152
	s_nop 0
	v_mov_b32_dpp v18, v18 quad_perm:[1,0,3,2] row_mask:0xf bank_mask:0xf
	v_cndmask_b32_e64 v19, v20, v18, s[40:41]
	v_cndmask_b32_e64 v18, v18, v21, s[40:41]
	v_cvt_pk_bf16_f32 v19, v19, v18
	v_cndmask_b32_e64 v18, v22, v23, s[38:39]
	ds_write_b32 v152, v19 offset:49408
	s_nop 0
	v_mov_b32_dpp v18, v18 quad_perm:[1,0,3,2] row_mask:0xf bank_mask:0xf
	v_cndmask_b32_e64 v19, v22, v18, s[40:41]
	v_cndmask_b32_e64 v18, v18, v23, s[40:41]
	v_cvt_pk_bf16_f32 v19, v19, v18
	v_cndmask_b32_e64 v18, v24, v25, s[38:39]
	ds_write_b32 v152, v19 offset:50176
	s_nop 0
	v_mov_b32_dpp v18, v18 quad_perm:[1,0,3,2] row_mask:0xf bank_mask:0xf
	v_cndmask_b32_e64 v19, v24, v18, s[40:41]
	v_cndmask_b32_e64 v18, v18, v25, s[40:41]
	v_cvt_pk_bf16_f32 v19, v19, v18
	v_cndmask_b32_e64 v18, v26, v27, s[38:39]
	ds_write_b32 v152, v19 offset:50432
	s_nop 0
	v_mov_b32_dpp v18, v18 quad_perm:[1,0,3,2] row_mask:0xf bank_mask:0xf
	v_cndmask_b32_e64 v19, v26, v18, s[40:41]
	v_cndmask_b32_e64 v18, v18, v27, s[40:41]
	v_cvt_pk_bf16_f32 v19, v19, v18
	v_cndmask_b32_e64 v18, v28, v29, s[38:39]
	ds_write_b32 v152, v19 offset:51200
	s_nop 0
	v_mov_b32_dpp v18, v18 quad_perm:[1,0,3,2] row_mask:0xf bank_mask:0xf
	v_cndmask_b32_e64 v19, v28, v18, s[40:41]
	v_cndmask_b32_e64 v18, v18, v29, s[40:41]
	v_cvt_pk_bf16_f32 v19, v19, v18
	v_cndmask_b32_e64 v18, v30, v31, s[38:39]
	ds_write_b32 v152, v19 offset:51456
	s_nop 0
	v_mov_b32_dpp v18, v18 quad_perm:[1,0,3,2] row_mask:0xf bank_mask:0xf
	v_cndmask_b32_e64 v19, v30, v18, s[40:41]
	v_cndmask_b32_e64 v18, v18, v31, s[40:41]
	v_cvt_pk_bf16_f32 v19, v19, v18
	v_cndmask_b32_e64 v18, v32, v33, s[38:39]
	ds_write_b32 v152, v19 offset:52224
	s_nop 0
	v_mov_b32_dpp v18, v18 quad_perm:[1,0,3,2] row_mask:0xf bank_mask:0xf
	v_cndmask_b32_e64 v42, v32, v18, s[40:41]
	v_cndmask_b32_e64 v18, v18, v33, s[40:41]
	v_cvt_pk_bf16_f32 v42, v42, v18
	v_cndmask_b32_e64 v18, v2, v3, s[38:39]
	ds_write_b32 v152, v42 offset:52480
	s_nop 0
	v_mov_b32_dpp v18, v18 quad_perm:[1,0,3,2] row_mask:0xf bank_mask:0xf
	v_cndmask_b32_e64 v19, v2, v18, s[40:41]
	v_cndmask_b32_e64 v18, v18, v3, s[40:41]
	v_cvt_pk_bf16_f32 v19, v19, v18
	v_cndmask_b32_e64 v2, v4, v5, s[38:39]
	ds_write_b32 v152, v19 offset:49216
	s_nop 0
	v_mov_b32_dpp v2, v2 quad_perm:[1,0,3,2] row_mask:0xf bank_mask:0xf
	v_cndmask_b32_e64 v3, v4, v2, s[40:41]
	v_cndmask_b32_e64 v2, v2, v5, s[40:41]
	v_cvt_pk_bf16_f32 v3, v3, v2
	v_cndmask_b32_e64 v2, v6, v7, s[38:39]
	ds_write_b32 v152, v3 offset:49472
	s_nop 0
	v_mov_b32_dpp v2, v2 quad_perm:[1,0,3,2] row_mask:0xf bank_mask:0xf
	v_cndmask_b32_e64 v3, v6, v2, s[40:41]
	v_cndmask_b32_e64 v2, v2, v7, s[40:41]
	v_cvt_pk_bf16_f32 v3, v3, v2
	v_cndmask_b32_e64 v2, v8, v9, s[38:39]
	ds_write_b32 v152, v3 offset:50240
	s_nop 0
	v_mov_b32_dpp v2, v2 quad_perm:[1,0,3,2] row_mask:0xf bank_mask:0xf
	v_cndmask_b32_e64 v3, v8, v2, s[40:41]
	v_cndmask_b32_e64 v2, v2, v9, s[40:41]
	v_cvt_pk_bf16_f32 v3, v3, v2
	v_cndmask_b32_e64 v2, v10, v11, s[38:39]
	ds_write_b32 v152, v3 offset:50496
	s_nop 0
	v_mov_b32_dpp v2, v2 quad_perm:[1,0,3,2] row_mask:0xf bank_mask:0xf
	v_cndmask_b32_e64 v3, v10, v2, s[40:41]
	v_cndmask_b32_e64 v2, v2, v11, s[40:41]
	v_cvt_pk_bf16_f32 v3, v3, v2
	v_cndmask_b32_e64 v2, v12, v13, s[38:39]
	ds_write_b32 v152, v3 offset:51264
	s_nop 0
	v_mov_b32_dpp v2, v2 quad_perm:[1,0,3,2] row_mask:0xf bank_mask:0xf
	v_cndmask_b32_e64 v3, v12, v2, s[40:41]
	v_cndmask_b32_e64 v2, v2, v13, s[40:41]
	v_cvt_pk_bf16_f32 v3, v3, v2
	v_cndmask_b32_e64 v2, v14, v15, s[38:39]
	ds_write_b32 v152, v3 offset:51520
	s_nop 0
	v_mov_b32_dpp v2, v2 quad_perm:[1,0,3,2] row_mask:0xf bank_mask:0xf
	v_cndmask_b32_e64 v3, v14, v2, s[40:41]
	v_cndmask_b32_e64 v2, v2, v15, s[40:41]
	v_cvt_pk_bf16_f32 v3, v3, v2
	v_cndmask_b32_e64 v2, v16, v17, s[38:39]
	ds_write_b32 v152, v3 offset:52288
	s_nop 0
	v_mov_b32_dpp v2, v2 quad_perm:[1,0,3,2] row_mask:0xf bank_mask:0xf
	s_and_saveexec_b64 s[12:13], s[40:41]
	s_xor_b64 s[12:13], exec, s[12:13]
	s_cbranch_execz .LBB0_2270
	v_cvt_pk_bf16_f32 v18, v2, v17
